# attention unit pipelining: next index read behind one early barrier; next unit decode + Q/K/V LDS-DMA issued before the current unit's epilogue arithmetic
# speedup vs baseline: 1.0081x; 1.0047x over previous
.Lpipe_part2:
	s_barrier
	ds_read_b128 v[4:7], v4
	v_cmp_eq_u32_e32 vcc, 0, v19
	s_waitcnt lgkmcnt(0)
	v_lshlrev_b32_e32 v10, 16, v4
	v_and_b32_e32 v4, 0xffff0000, v4
	v_mul_f32_e32 v11, v4, v4
	v_fmac_f32_e32 v11, v10, v10
	v_lshlrev_b32_e32 v4, 16, v5
	v_fmac_f32_e32 v11, v4, v4
	v_and_b32_e32 v4, 0xffff0000, v5
	v_fmac_f32_e32 v11, v4, v4
	v_lshlrev_b32_e32 v4, 16, v6
	v_fmac_f32_e32 v11, v4, v4
	v_and_b32_e32 v4, 0xffff0000, v6
	v_fmac_f32_e32 v11, v4, v4
	v_lshlrev_b32_e32 v4, 16, v7
	v_fmac_f32_e32 v11, v4, v4
	v_and_b32_e32 v4, 0xffff0000, v7
	v_fmac_f32_e32 v11, v4, v4
	v_bitop3_b32 v4, v9, v8, 1 bitop3:0x36
	v_lshl_add_u32 v4, v4, 4, v3
	ds_read_b128 v[4:7], v4
	s_waitcnt lgkmcnt(0)
	v_lshlrev_b32_e32 v10, 16, v4
	v_fmac_f32_e32 v11, v10, v10
	v_and_b32_e32 v4, 0xffff0000, v4
	v_fmac_f32_e32 v11, v4, v4
	v_lshlrev_b32_e32 v4, 16, v5
	v_fmac_f32_e32 v11, v4, v4
	v_and_b32_e32 v4, 0xffff0000, v5
	v_fmac_f32_e32 v11, v4, v4
	v_lshlrev_b32_e32 v4, 16, v6
	v_fmac_f32_e32 v11, v4, v4
	v_and_b32_e32 v4, 0xffff0000, v6
	v_fmac_f32_e32 v11, v4, v4
	v_lshlrev_b32_e32 v4, 16, v7
	v_fmac_f32_e32 v11, v4, v4
	v_and_b32_e32 v4, 0xffff0000, v7
	v_fmac_f32_e32 v11, v4, v4
	v_bitop3_b32 v4, v9, v8, 2 bitop3:0x36
	v_lshl_add_u32 v4, v4, 4, v3
	ds_read_b128 v[4:7], v4
	s_waitcnt lgkmcnt(0)
	v_lshlrev_b32_e32 v10, 16, v4
	v_fmac_f32_e32 v11, v10, v10
	v_and_b32_e32 v4, 0xffff0000, v4
	v_fmac_f32_e32 v11, v4, v4
	v_lshlrev_b32_e32 v4, 16, v5
	v_fmac_f32_e32 v11, v4, v4
	v_and_b32_e32 v4, 0xffff0000, v5
	v_fmac_f32_e32 v11, v4, v4
	v_lshlrev_b32_e32 v4, 16, v6
	v_fmac_f32_e32 v11, v4, v4
	v_and_b32_e32 v4, 0xffff0000, v6
	v_fmac_f32_e32 v11, v4, v4
	v_lshlrev_b32_e32 v4, 16, v7
	v_fmac_f32_e32 v11, v4, v4
	v_and_b32_e32 v4, 0xffff0000, v7
	v_fmac_f32_e32 v11, v4, v4
	v_bitop3_b32 v4, v9, v8, 3 bitop3:0x36
	v_lshl_add_u32 v3, v4, 4, v3
	ds_read_b128 v[4:7], v3
	s_waitcnt lgkmcnt(0)
	v_lshlrev_b32_e32 v3, 16, v4
	v_fmac_f32_e32 v11, v3, v3
	v_and_b32_e32 v3, 0xffff0000, v4
	v_fmac_f32_e32 v11, v3, v3
	v_lshlrev_b32_e32 v3, 16, v5
	v_fmac_f32_e32 v11, v3, v3
	v_and_b32_e32 v3, 0xffff0000, v5
	v_fmac_f32_e32 v11, v3, v3
	v_lshlrev_b32_e32 v3, 16, v6
	v_fmac_f32_e32 v11, v3, v3
	v_and_b32_e32 v3, 0xffff0000, v6
	v_fmac_f32_e32 v11, v3, v3
	v_lshlrev_b32_e32 v3, 16, v7
	v_fmac_f32_e32 v11, v3, v3
	v_and_b32_e32 v3, 0xffff0000, v7
	v_fmac_f32_e32 v11, v3, v3
	ds_bpermute_b32 v3, v221, v11
	s_waitcnt lgkmcnt(0)
	v_max_f32_e32 v3, v3, v3
	v_max_f32_e32 v3, v11, v3
	ds_bpermute_b32 v4, v222, v3
	s_waitcnt lgkmcnt(0)
	v_max_f32_e32 v4, v4, v4
	v_max_f32_e32 v3, v3, v4
	ds_bpermute_b32 v4, v223, v3
	s_waitcnt lgkmcnt(0)
	v_max_f32_e32 v4, v4, v4
	v_max_f32_e32 v3, v3, v4
	ds_bpermute_b32 v4, v224, v3
	s_waitcnt lgkmcnt(0)
	v_max_f32_e32 v4, v4, v4
	v_max_f32_e32 v3, v3, v4
	ds_bpermute_b32 v4, v225, v3
	s_waitcnt lgkmcnt(0)
	v_max_f32_e32 v4, v4, v4
	v_max_f32_e32 v3, v3, v4
	ds_bpermute_b32 v4, v226, v3
	s_and_saveexec_b64 s[4:5], vcc
	s_cbranch_execz .LBB0_300
	s_waitcnt lgkmcnt(0)
	v_max_f32_e32 v4, v4, v4
	v_max_f32_e32 v3, v3, v3
	v_readlane_b32 s13, v245, 26
	v_max_f32_e32 v3, v3, v4
	s_nop 0
	v_mov_b32_e32 v4, s13
	ds_write_b32 v4, v3
	v_mov_b32_e32 v246, 0x18080
	v_mov_b32_e32 v247, 0
	ds_write_b32 v246, v247

.LBB0_349:
	v_mov_b32_e32 v228, 0x2000
	v_mov_b32_e32 v229, 0x7000
	v_mov_b32_e32 v230, 1
	v_mov_b32_e32 v231, 0x3f4ccccd
	v_mov_b32_e32 v232, 0x260
	v_mov_b32_e32 v233, 0x3727c5ac
	v_mov_b32_e32 v234, 0x7f800000
	v_mov_b32_e32 v235, 0x3fb8aa3b
	v_mov_b32_e32 v236, 0xa0
	v_mov_b32_e32 v237, 0xa1
	v_mov_b32_e32 v238, 0x7fc00000
	v_readlane_b32 s87, v244, 26
	s_movk_i32 s88, 0x600
	v_readlane_b32 s89, v244, 21
	s_mov_b32 s90, 0x46000000
	s_and_b64 vcc, exec, s[92:93]
	s_cbranch_vccnz .Lpipe_pub_done
	v_mov_b32_e32 v0, v220
	s_nop 0
	v_cmp_eq_u32_e32 vcc, 0, v0
	s_and_saveexec_b64 s[2:3], vcc
	v_mov_b32_e32 v0, s87
	ds_write_b32 v0, v184
	s_or_b64 exec, exec, s[2:3]
.Lpipe_pub_done:
	v_mov_b32_e32 v0, s87
	s_waitcnt lgkmcnt(0)
	s_barrier
	ds_read_b32 v0, v0
	v_readlane_b32 s2, v245, 12
	v_readlane_b32 s3, v245, 14
	s_waitcnt lgkmcnt(0)
	v_readfirstlane_b32 s4, v0
	s_cmp_ge_i32 s4, s2
	s_cbranch_scc1 .LBB0_351
	s_cmpk_gt_i32 s4, 0x4f
	s_cselect_b64 s[12:13], -1, 0
	s_cmp_lt_u32 s4, s3
	s_cselect_b64 s[2:3], -1, 0
	s_and_b64 s[2:3], s[2:3], s[12:13]
	s_and_b64 vcc, exec, s[2:3]
	s_cbranch_vccnz .LBB0_351
	s_mov_b32 s46, s4
	s_and_b64 vcc, exec, s[92:93]
	s_cbranch_vccnz .Lpipe_nofetch
	v_mov_b32_e32 v0, v220
	s_nop 0
	v_cmp_eq_u32_e32 vcc, 0, v0
	s_and_saveexec_b64 s[2:3], vcc
	s_cbranch_execz .Lpipe_fetch_done
	s_mov_b64 s[12:13], exec
	v_mbcnt_lo_u32_b32 v0, s12, 0
	v_mbcnt_hi_u32_b32 v0, s13, v0
	v_cmp_eq_u32_e32 vcc, 0, v0
	s_and_saveexec_b64 s[4:5], vcc
	s_cbranch_execz .Lpipe_fetch_in
	s_bcnt1_i32_b64 s12, s[12:13]
	v_mov_b32_e32 v2, s12
	global_atomic_add v184, v1, v2, s[70:71] sc0

.Lpipe_nofetch:
	s_add_u32 s2, s78, s8
	s_addc_u32 s3, s79, s9
	v_ashrrev_i32_e32 v173, 31, v172
	v_lshl_add_u64 v[2:3], v[172:173], 2, s[2:3]
	v_mov_b32_e32 v0, v175
	global_load_dwordx4 v[94:97], v[2:3], off
	global_load_dwordx4 v[90:93], v[2:3], off offset:32
	global_load_dwordx4 v[86:89], v[2:3], off offset:64
	global_load_dwordx4 v[82:85], v[2:3], off offset:96
	global_load_dwordx4 v[14:17], v[2:3], off offset:128
	global_load_dwordx4 v[10:13], v[2:3], off offset:160
	global_load_dwordx4 v[6:9], v[2:3], off offset:192
	s_nop 0
	global_load_dwordx4 v[2:5], v[2:3], off offset:224
	v_mov_b32_e32 v147, 0
	s_cmpk_gt_i32 s46, 0x4f
	v_readlane_b32 s2, v245, 13
	s_cselect_b32 s2, s2, 0
	s_sub_i32 s2, s46, s2
	s_bfe_u32 s4, s2, 0x30001
	s_and_b32 s3, s2, 1
	s_xor_b32 s5, s4, 7
	s_or_b32 s4, s4, 8
	s_cmp_eq_u32 s3, 0
	s_cselect_b32 s3, s4, s5
	s_mov_b64 s[4:5], s[0:1]
	s_mov_b64 s[12:13], s[0:1]
	s_load_dwordx2 s[4:5], s[4:5], 0x80
	s_mov_b64 s[12:13], s[0:1]
	s_ashr_i32 s2, s2, 4
	s_sub_i32 s12, 8, s2
	v_cvt_f32_i32_e32 v146, s12
	v_mov_b32_e32 v156, v220
	v_readlane_b32 s13, v245, 17
	v_exp_f32_e64 v146, -v146
	s_sub_i32 s55, 7, s2
	s_lshl_b32 s55, s55, 6
	v_ashrrev_i32_e32 v148, 5, v156
	v_readfirstlane_b32 s12, v146
	v_ashrrev_i32_e32 v146, 3, v156
	v_add_u32_e32 v146, s13, v146
	v_mul_lo_u32 v149, v146, s88
	v_lshrrev_b32_e32 v146, 1, v146
	s_add_i32 s13, s55, 0x200
	v_xor_b32_e32 v146, v146, v156
	v_add_u32_e32 v149, s13, v149
	v_lshlrev_b32_e32 v146, 3, v146
	v_readlane_b32 s13, v245, 16
	v_and_or_b32 v146, v146, 56, v149
	v_lshlrev_b32_e32 v150, 3, v156
	v_lshl_add_u32 v149, v148, 3, s13
	v_readlane_b32 s13, v245, 18
	s_add_i32 s13, s13, s55
	v_and_b32_e32 v157, 24, v150
	v_or_b32_e32 v155, s13, v157
	v_readlane_b32 s13, v245, 19
	s_waitcnt lgkmcnt(0)
	s_add_u32 s4, s4, s13
	s_addc_u32 s5, s5, 0
	s_add_u32 s60, s4, 0x13200000
	s_addc_u32 s61, s5, 0
	s_mul_i32 s4, s3, 0xc0000
	s_add_u32 s80, s60, s4
	v_lshlrev_b32_e32 v146, 1, v146
	s_addc_u32 s81, s61, 0
	s_movk_i32 s4, 0xfc00
	v_lshl_add_u64 v[150:151], s[80:81], 0, v[146:147]
	s_mov_b32 s5, -1
	v_lshl_add_u64 v[152:153], v[150:151], 0, s[4:5]
	v_readlane_b32 s5, v245, 22
	s_mov_b32 s4, m0
	s_mov_b32 m0, s5
	s_nop 0
	global_load_lds_dwordx4 v[152:153], off
	s_mov_b32 m0, s4
	s_mov_b64 s[4:5], 0x2fc00
	v_bfe_u32 v154, v156, 2, 3
	v_lshl_add_u64 v[152:153], v[150:151], 0, s[4:5]
	v_readlane_b32 s5, v245, 20
	s_mov_b32 s4, m0
	s_mov_b32 m0, s5
	s_nop 0
	global_load_lds_dwordx4 v[152:153], off
	s_mov_b32 m0, s4
	s_mov_b64 s[4:5], 0x5fc00
	v_or_b32_e32 v149, v149, v154
	v_lshl_add_u64 v[152:153], v[150:151], 0, s[4:5]
	v_readlane_b32 s5, v245, 21
	s_mov_b32 s4, m0
	s_mov_b32 m0, s5
	s_nop 0
	global_load_lds_dwordx4 v[152:153], off
	s_mov_b32 m0, s4
	s_mov_b64 s[4:5], 0x8fc00
	v_mul_lo_u32 v149, v149, s88
	v_lshl_add_u64 v[152:153], v[150:151], 0, s[4:5]
	v_readlane_b32 s5, v245, 23
	s_mov_b32 s4, m0
	s_mov_b32 m0, s5
	s_nop 0
	global_load_lds_dwordx4 v[152:153], off
	s_mov_b32 m0, s4
	v_add_lshl_u32 v170, v155, v149, 1
	s_mov_b32 s4, m0
	s_mov_b32 m0, s64
	s_nop 0
	global_load_lds_dwordx4 v[150:151], off
	s_mov_b32 m0, s4
	v_mov_b32_e32 v171, v1
	v_lshl_add_u64 v[150:151], s[80:81], 0, v[170:171]
	v_readlane_b32 s5, v245, 24
	s_mov_b32 s4, m0
	s_mov_b32 m0, s5
	s_nop 0
	global_load_lds_dwordx4 v[150:151], off
	s_mov_b32 m0, s4
	v_lshlrev_b32_e32 v150, 2, v156
	v_readlane_b32 s4, v245, 25
	v_and_b32_e32 v155, 4, v150
	v_bitop3_b32 v150, v150, v154, 4 bitop3:0x6c
	v_lshl_add_u32 v149, v156, 6, s4
	v_and_b32_e32 v149, 0xffffff80, v149
	v_add_u32_e32 v149, s63, v149
	v_lshl_add_u32 v150, v150, 4, v149
	s_ashr_i32 s101, s2, 31
	s_mov_b32 s100, s2
	s_lshl_b64 s[100:101], s[100:101], 2
	s_sub_u32 s100, s7, s100
	s_subb_u32 s101, s33, s101
	v_mov_b32_e32 v248, 0
	global_load_dword v249, v248, s[100:101] offset:28 sc1
	s_add_u32 s100, s80, 0x30000
	s_addc_u32 s101, s81, 0
	v_lshl_add_u64 v[250:251], s[100:101], 0, v[146:147]
	v_lshl_add_u64 v[252:253], s[100:101], 0, v[170:171]
	v_readlane_b32 s98, v245, 27
	s_mov_b32 s99, m0
	s_mov_b32 m0, s98
	s_nop 0
	global_load_lds_dwordx4 v[250:251], off
	v_readlane_b32 s98, v245, 28
	s_nop 0
	s_mov_b32 m0, s98
	s_nop 0
	global_load_lds_dwordx4 v[252:253], off
	s_add_u32 s100, s80, 0x60000
	s_addc_u32 s101, s81, 0
	v_lshl_add_u64 v[250:251], s[100:101], 0, v[146:147]
	v_lshl_add_u64 v[252:253], s[100:101], 0, v[170:171]
	v_readlane_b32 s98, v245, 29
	s_nop 0
	s_mov_b32 m0, s98
	s_nop 0
	global_load_lds_dwordx4 v[250:251], off
	v_readlane_b32 s98, v245, 30
	s_nop 0
	s_mov_b32 m0, s98
	s_nop 0
	global_load_lds_dwordx4 v[252:253], off
	s_mov_b32 m0, s99
	s_mov_b32 s4, s2
	s_mov_b32 s5, s3
	s_ashr_i32 s77, s76, 31
	v_permlane32_swap_b32_e32 v175, v0
	s_nop 0
	v_add_f32_e32 v0, v175, v0
	v_div_scale_f32 v98, s[2:3], v0, v0, 1.0
	v_rcp_f32_e32 v99, v98
	s_nop 0
	v_fma_f32 v100, -v98, v99, 1.0
	v_fmac_f32_e32 v99, v100, v99
	v_div_scale_f32 v100, vcc, 1.0, v0, 1.0
	v_mul_f32_e32 v101, v100, v99
	v_fma_f32 v102, -v98, v101, v100
	v_fmac_f32_e32 v101, v102, v99
	v_fma_f32 v98, -v98, v101, v100
	v_div_fmas_f32 v98, v98, v99, v101
	v_div_fixup_f32 v0, v98, v0, 1.0
	v_mov_b32_e32 v98, v174
	s_nop 1
	v_permlane32_swap_b32_e32 v174, v98
	s_nop 0
	v_add_f32_e32 v98, v174, v98
	v_div_scale_f32 v99, s[2:3], v98, v98, 1.0
	v_rcp_f32_e32 v100, v99
	s_mov_b32 s2, 0xf800000
	v_fma_f32 v101, -v99, v100, 1.0
	v_fmac_f32_e32 v100, v101, v100
	v_div_scale_f32 v101, vcc, 1.0, v98, 1.0
	v_mul_f32_e32 v102, v101, v100
	v_fma_f32 v103, -v99, v102, v101
	v_fmac_f32_e32 v102, v103, v100
	v_fma_f32 v99, -v99, v102, v101
	v_div_fmas_f32 v99, v99, v100, v102
	v_div_fixup_f32 v98, v99, v98, 1.0
	v_mul_f32_e32 v98, v183, v98
	v_mul_f32_e32 v66, v66, v98
	v_fma_f32 v50, v50, v0, -v66
	v_mul_f32_e32 v66, v67, v98
	v_fma_f32 v51, v51, v0, -v66
	v_mul_f32_e32 v66, v51, v51
	v_mul_f32_e32 v67, v68, v98
	v_fmac_f32_e32 v66, v50, v50
	v_fma_f32 v52, v52, v0, -v67
	v_mul_f32_e32 v67, v69, v98
	v_fmac_f32_e32 v66, v52, v52
	v_fma_f32 v53, v53, v0, -v67
	v_mul_f32_e32 v67, v70, v98
	v_fmac_f32_e32 v66, v53, v53
	v_fma_f32 v54, v54, v0, -v67
	v_mul_f32_e32 v67, v71, v98
	v_fmac_f32_e32 v66, v54, v54
	v_fma_f32 v55, v55, v0, -v67
	v_mul_f32_e32 v67, v72, v98
	v_fmac_f32_e32 v66, v55, v55
	v_fma_f32 v56, v56, v0, -v67
	v_mul_f32_e32 v67, v73, v98
	v_fmac_f32_e32 v66, v56, v56
	v_fma_f32 v57, v57, v0, -v67
	v_mul_f32_e32 v67, v74, v98
	v_fmac_f32_e32 v66, v57, v57
	v_fma_f32 v58, v58, v0, -v67
	v_mul_f32_e32 v67, v75, v98
	v_fmac_f32_e32 v66, v58, v58
	v_fma_f32 v59, v59, v0, -v67
	v_mul_f32_e32 v67, v76, v98
	v_fmac_f32_e32 v66, v59, v59
	v_fma_f32 v60, v60, v0, -v67
	v_mul_f32_e32 v67, v77, v98
	v_fmac_f32_e32 v66, v60, v60
	v_fma_f32 v61, v61, v0, -v67
	v_mul_f32_e32 v67, v78, v98
	v_fmac_f32_e32 v66, v61, v61
	v_fma_f32 v62, v62, v0, -v67
	v_mul_f32_e32 v67, v79, v98
	v_fmac_f32_e32 v66, v62, v62
	v_fma_f32 v63, v63, v0, -v67
	v_mul_f32_e32 v67, v80, v98
	v_fmac_f32_e32 v66, v63, v63
	v_fma_f32 v64, v64, v0, -v67
	v_mul_f32_e32 v67, v81, v98
	v_fmac_f32_e32 v66, v64, v64
	v_fma_f32 v65, v65, v0, -v67
	v_mul_f32_e32 v34, v34, v98
	v_fmac_f32_e32 v66, v65, v65
	v_fma_f32 v34, v18, v0, -v34
	v_mul_f32_e32 v18, v35, v98
	v_fmac_f32_e32 v66, v34, v34
	v_fma_f32 v35, v19, v0, -v18
	v_mul_f32_e32 v18, v36, v98
	v_fmac_f32_e32 v66, v35, v35
	v_fma_f32 v36, v20, v0, -v18
	v_mul_f32_e32 v18, v37, v98
	v_fmac_f32_e32 v66, v36, v36
	v_fma_f32 v37, v21, v0, -v18
	v_mul_f32_e32 v18, v38, v98
	v_fmac_f32_e32 v66, v37, v37
	v_fma_f32 v38, v22, v0, -v18
	v_mul_f32_e32 v18, v39, v98
	v_fmac_f32_e32 v66, v38, v38
	v_fma_f32 v39, v23, v0, -v18
	v_mul_f32_e32 v18, v40, v98
	v_fmac_f32_e32 v66, v39, v39
	v_fma_f32 v24, v24, v0, -v18
	v_mul_f32_e32 v18, v41, v98
	v_fmac_f32_e32 v66, v24, v24
	v_fma_f32 v25, v25, v0, -v18
	v_mul_f32_e32 v18, v42, v98
	v_fmac_f32_e32 v66, v25, v25
	v_fma_f32 v26, v26, v0, -v18
	v_mul_f32_e32 v18, v43, v98
	v_fmac_f32_e32 v66, v26, v26
	v_fma_f32 v27, v27, v0, -v18
	v_mul_f32_e32 v18, v44, v98
	v_fmac_f32_e32 v66, v27, v27
	v_fma_f32 v28, v28, v0, -v18
	v_mul_f32_e32 v18, v45, v98
	v_fmac_f32_e32 v66, v28, v28
	v_fma_f32 v29, v29, v0, -v18
	v_mul_f32_e32 v18, v46, v98
	v_fmac_f32_e32 v66, v29, v29
	v_fma_f32 v30, v30, v0, -v18
	v_mul_f32_e32 v18, v47, v98
	v_fmac_f32_e32 v66, v30, v30
	v_fma_f32 v31, v31, v0, -v18
	v_mul_f32_e32 v18, v48, v98
	v_fmac_f32_e32 v66, v31, v31
	v_fma_f32 v32, v32, v0, -v18
	v_mul_f32_e32 v18, v49, v98
	v_fmac_f32_e32 v66, v32, v32
	v_fma_f32 v33, v33, v0, -v18
	v_fmac_f32_e32 v66, v33, v33
	v_mov_b32_e32 v0, v66
	s_nop 1
	v_permlane32_swap_b32_e32 v66, v0
	s_nop 0
	v_add_f32_e32 v0, v66, v0
	v_fmamk_f32 v0, v0, 0x3c800000, v233
	v_cmp_gt_f32_e32 vcc, s2, v0
	v_mul_f32_e32 v18, 0x4f800000, v0
	s_nop 0
	v_cndmask_b32_e32 v0, v0, v18, vcc
	v_sqrt_f32_e32 v18, v0
	s_nop 0
	v_add_u32_e32 v19, -1, v18
	v_fma_f32 v20, -v19, v18, v0
	v_cmp_ge_f32_e64 s[2:3], 0, v20
	v_add_u32_e32 v20, 1, v18
	s_nop 0
	v_cndmask_b32_e64 v19, v18, v19, s[2:3]
	v_fma_f32 v18, -v20, v18, v0
	v_cmp_lt_f32_e64 s[2:3], 0, v18
	s_nop 1
	v_cndmask_b32_e64 v18, v19, v20, s[2:3]
	v_mul_f32_e32 v19, 0x37800000, v18
	v_cndmask_b32_e32 v18, v18, v19, vcc
	v_cmp_class_f32_e32 vcc, v0, v232
	s_nop 1
	v_cndmask_b32_e32 v0, v18, v0, vcc
	v_div_scale_f32 v18, s[2:3], v0, v0, v177
	v_rcp_f32_e32 v19, v18
	v_readlane_b32 s2, v244, 1
	s_add_i32 s2, s2, s68
	v_fma_f32 v20, -v18, v19, 1.0
	v_fmac_f32_e32 v19, v20, v19
	v_div_scale_f32 v20, vcc, v177, v0, v177
	v_mul_f32_e32 v21, v20, v19
	v_fma_f32 v22, -v18, v21, v20
	v_fmac_f32_e32 v21, v22, v19
	v_fma_f32 v18, -v18, v21, v20
	v_div_fmas_f32 v18, v18, v19, v21
	v_div_fixup_f32 v40, v18, v0, v177
	v_or_b32_e32 v0, s2, v185
	v_lshlrev_b64 v[18:19], 11, v[0:1]
	v_lshl_add_u64 v[18:19], s[74:75], 0, v[18:19]
	v_lshl_add_u64 v[18:19], s[76:77], 1, v[18:19]
	v_mul_f32_e32 v0, v50, v40
	v_mul_f32_e32 v20, v51, v40
	v_lshl_add_u64 v[18:19], v[172:173], 1, v[18:19]
	s_mov_b64 s[2:3], 0xb200000
	s_waitcnt vmcnt(18)
	v_mul_f32_e32 v0, v94, v0
	v_mul_f32_e32 v20, v95, v20
	v_lshl_add_u64 v[22:23], v[18:19], 0, s[2:3]
	s_mov_b32 s2, 0xb200000
	v_cvt_pk_bf16_f32 v20, v0, v20
	v_mul_f32_e32 v0, v52, v40
	v_mul_f32_e32 v21, v53, v40
	v_add_co_u32_e32 v18, vcc, s2, v18
	v_mul_f32_e32 v0, v96, v0
	v_mul_f32_e32 v21, v97, v21
	v_addc_co_u32_e32 v19, vcc, 0, v19, vcc
	v_cvt_pk_bf16_f32 v21, v0, v21
	global_store_dwordx2 v[18:19], v[20:21], off
	v_mul_f32_e32 v0, v54, v40
	v_mul_f32_e32 v18, v55, v40
	s_waitcnt vmcnt(18)
	v_mul_f32_e32 v0, v90, v0
	v_mul_f32_e32 v18, v91, v18
	v_cvt_pk_bf16_f32 v18, v0, v18
	v_mul_f32_e32 v0, v56, v40
	v_mul_f32_e32 v19, v57, v40
	v_mul_f32_e32 v0, v92, v0
	v_mul_f32_e32 v19, v93, v19
	v_cvt_pk_bf16_f32 v19, v0, v19
	global_store_dwordx2 v[22:23], v[18:19], off offset:16
	v_mul_f32_e32 v0, v58, v40
	v_mul_f32_e32 v18, v59, v40
	s_waitcnt vmcnt(18)
	v_mul_f32_e32 v0, v86, v0
	v_mul_f32_e32 v18, v87, v18
	v_cvt_pk_bf16_f32 v18, v0, v18
	v_mul_f32_e32 v0, v60, v40
	v_mul_f32_e32 v19, v61, v40
	v_mul_f32_e32 v0, v88, v0
	v_mul_f32_e32 v19, v89, v19
	v_cvt_pk_bf16_f32 v19, v0, v19
	global_store_dwordx2 v[22:23], v[18:19], off offset:32
	v_mul_f32_e32 v0, v62, v40
	v_mul_f32_e32 v18, v63, v40
	s_waitcnt vmcnt(18)
	v_mul_f32_e32 v0, v82, v0
	v_mul_f32_e32 v18, v83, v18
	v_cvt_pk_bf16_f32 v18, v0, v18
	v_mul_f32_e32 v0, v64, v40
	v_mul_f32_e32 v19, v65, v40
	v_mul_f32_e32 v0, v84, v0
	v_mul_f32_e32 v19, v85, v19
	v_cvt_pk_bf16_f32 v19, v0, v19
	v_mul_f32_e32 v0, v34, v40
	s_waitcnt vmcnt(17)
	v_mul_f32_e32 v0, v14, v0
	v_mul_f32_e32 v14, v35, v40
	v_mul_f32_e32 v14, v15, v14
	global_store_dwordx2 v[22:23], v[18:19], off offset:48
	v_cvt_pk_bf16_f32 v14, v0, v14
	v_mul_f32_e32 v0, v36, v40
	v_mul_f32_e32 v15, v37, v40
	v_mul_f32_e32 v0, v16, v0
	v_mul_f32_e32 v15, v17, v15
	v_cvt_pk_bf16_f32 v15, v0, v15
	v_mul_f32_e32 v0, v38, v40
	s_waitcnt vmcnt(17)
	v_mul_f32_e32 v0, v10, v0
	v_mul_f32_e32 v10, v39, v40
	v_mul_f32_e32 v10, v11, v10
	global_store_dwordx2 v[22:23], v[14:15], off offset:64
	v_cvt_pk_bf16_f32 v10, v0, v10
	v_mul_f32_e32 v0, v24, v40
	v_mul_f32_e32 v11, v25, v40
	v_mul_f32_e32 v0, v12, v0
	v_mul_f32_e32 v11, v13, v11
	v_cvt_pk_bf16_f32 v11, v0, v11
	v_mul_f32_e32 v0, v26, v40
	s_waitcnt vmcnt(17)
	v_mul_f32_e32 v0, v6, v0
	v_mul_f32_e32 v6, v27, v40
	v_mul_f32_e32 v6, v7, v6
	global_store_dwordx2 v[22:23], v[10:11], off offset:80
	v_cvt_pk_bf16_f32 v6, v0, v6
	v_mul_f32_e32 v0, v28, v40
	v_mul_f32_e32 v7, v29, v40
	v_mul_f32_e32 v0, v8, v0
	v_mul_f32_e32 v7, v9, v7
	v_cvt_pk_bf16_f32 v7, v0, v7
	v_mul_f32_e32 v0, v30, v40
	s_waitcnt vmcnt(17)
	v_mul_f32_e32 v0, v2, v0
	v_mul_f32_e32 v2, v31, v40
	v_mul_f32_e32 v2, v3, v2
	v_mul_f32_e32 v3, v33, v40
	global_store_dwordx2 v[22:23], v[6:7], off offset:96
	v_cvt_pk_bf16_f32 v2, v0, v2
	v_mul_f32_e32 v0, v32, v40
	v_mul_f32_e32 v3, v5, v3
	v_mul_f32_e32 v0, v4, v0
	v_cvt_pk_bf16_f32 v3, v0, v3
	global_store_dwordx2 v[22:23], v[2:3], off offset:112
	s_mov_b32 s2, s4
	s_mov_b32 s3, s5
	s_mov_b32 s76, s55
	v_mov_b32_e32 v0, v146
	v_mov_b32_e32 v2, v148
	v_mov_b32_e32 v3, v149
	v_mov_b32_e32 v4, v150
	v_mov_b32_e32 v8, v154
	v_mov_b32_e32 v9, v155
	v_mov_b32_e32 v19, v156
	v_mov_b32_e32 v20, v157
	s_waitcnt vmcnt(13)
	s_branch .Lpipe_part2
